# attention chunk loop head aligned to a 64-byte fetch line
# baseline (speedup 1.0000x reference)
.LBB0_207:
	v_ashrrev_i32_e32 v184, 3, v2
	v_add_u32_e32 v3, s0, v184
	v_mov_b64_e32 v[4:5], s[92:93]
	v_mad_i64_i32 v[6:7], s[6:7], v3, s28, v[4:5]
	v_lshlrev_b32_e32 v0, 3, v2
	v_add_u32_e32 v3, 32, v3
	s_lshl_b32 s26, s3, 1
	v_and_b32_e32 v44, 56, v0
	v_mad_i64_i32 v[4:5], s[6:7], v3, s28, v[4:5]
	v_lshl_add_u64 v[6:7], v[6:7], 0, s[26:27]
	v_lshlrev_b32_e32 v0, 1, v44
	v_lshl_add_u64 v[4:5], v[4:5], 0, s[26:27]
	v_lshl_add_u64 v[6:7], v[6:7], 0, v[0:1]
	v_lshl_add_u64 v[4:5], v[4:5], 0, v[0:1]
	v_readlane_b32 s6, v250, 10
	v_ashrrev_i32_e32 v45, 2, v2
	v_readlane_b32 s7, v250, 11
	v_lshlrev_b32_e32 v3, 1, v2
	v_add_u32_e32 v6, s3, v45
	v_mov_b64_e32 v[4:5], s[6:7]
	s_ashr_i32 s1, s0, 31
	v_and_b32_e32 v75, 6, v3
	v_mad_i64_i32 v[166:167], s[6:7], v6, s19, v[4:5]
	v_mov_b32_e32 v7, v1
	v_lshlrev_b32_e32 v6, 4, v75
	v_lshl_add_u64 v[4:5], s[0:1], 1, v[166:167]
	v_lshl_add_u64 v[4:5], v[4:5], 0, v[6:7]
	v_lshrrev_b32_e32 v3, 1, v184
	v_and_b32_e32 v179, 15, v2
	v_bfe_u32 v178, v2, 4, 2
	v_xor_b32_e32 v2, v3, v2
	v_lshl_add_u32 v185, v44, 2, 0
	v_mov_b32_e32 v165, 0
	s_cmp_lt_i32 s13, -3
	v_mov_b32_e32 v164, 0
	v_mov_b32_e32 v163, 0
	v_mov_b32_e32 v162, 0
	v_mov_b32_e32 v85, 0
	v_mov_b32_e32 v84, v165
	v_mov_b32_e32 v83, v165
	v_mov_b32_e32 v82, v165
	v_mov_b32_e32 v81, 0
	v_mov_b32_e32 v80, v165
	v_mov_b32_e32 v79, v165
	v_mov_b32_e32 v78, v165
	v_mov_b32_e32 v73, 0
	v_mov_b32_e32 v72, v165
	v_mov_b32_e32 v71, v165
	v_mov_b32_e32 v70, v165
	v_mov_b32_e32 v53, 0
	v_mov_b32_e32 v52, v165
	v_mov_b32_e32 v51, v165
	v_mov_b32_e32 v50, v165
	v_mov_b32_e32 v49, 0
	v_mov_b32_e32 v48, v165
	v_mov_b32_e32 v47, v165
	v_mov_b32_e32 v46, v165
	v_mov_b32_e32 v44, v165
	v_lshlrev_b32_e32 v32, 3, v2
	v_lshlrev_b32_e32 v30, 6, v184
	v_and_or_b32 v186, v32, 56, v30
	v_or_b32_e32 v31, 1, v75
	v_mov_b32_e32 v43, v165
	v_mov_b32_e32 v42, v165
	v_mov_b32_e32 v41, 0
	v_mov_b32_e32 v40, v165
	v_mov_b32_e32 v39, v165
	v_mov_b32_e32 v38, v165
	v_mov_b32_e32 v37, 0
	v_mov_b32_e32 v36, v165
	v_mov_b32_e32 v35, v165
	v_mov_b32_e32 v34, v165
	v_lshl_add_u32 v29, v186, 1, 0
	s_waitcnt vmcnt(3)
	ds_write_b128 v29, v[54:57]
	s_waitcnt vmcnt(2)
	ds_write_b128 v29, v[58:61] offset:4096
	v_mov_b32_e32 v33, 0
	v_lshrrev_b32_e32 v3, 1, v45
	v_lshlrev_b32_e32 v2, 6, v45
	v_bitop3_b32 v4, v3, v75, 7 bitop3:0x6c
	v_bitop3_b32 v3, v3, v31, 7 bitop3:0x6c
	v_lshl_or_b32 v187, v4, 3, v2
	v_lshl_or_b32 v188, v3, 3, v2
	v_lshl_add_u32 v4, v187, 1, 0
	v_lshl_add_u32 v2, v188, 1, 0
	s_waitcnt vmcnt(0)
	ds_write_b128 v4, v[66:69] offset:16384
	ds_write_b128 v2, v[62:65] offset:16384
	v_mov_b32_e32 v45, 0
	v_mov_b32_e32 v32, v165
	v_mov_b32_e32 v31, v165
	v_mov_b32_e32 v30, v165
	v_mov_b32_e32 v29, 0
	v_mov_b32_e32 v28, v165
	v_mov_b32_e32 v27, v165
	v_mov_b32_e32 v26, v165
	v_mov_b32_e32 v25, 0
	v_mov_b32_e32 v24, v165
	v_mov_b32_e32 v23, v165
	v_mov_b32_e32 v22, v165
	v_mov_b32_e32 v21, 0
	v_mov_b32_e32 v20, v165
	v_mov_b32_e32 v19, v165
	v_mov_b32_e32 v18, v165
	v_mov_b32_e32 v17, 0
	v_mov_b32_e32 v16, v165
	v_mov_b32_e32 v15, v165
	v_mov_b32_e32 v14, v165
	v_mov_b32_e32 v13, 0
	v_mov_b32_e32 v12, v165
	v_mov_b32_e32 v11, v165
	v_mov_b32_e32 v10, v165
	v_mov_b32_e32 v9, 0
	v_mov_b32_e32 v8, v165
	v_mov_b32_e32 v7, v165
	v_mov_b32_e32 v6, v165
	v_mov_b32_e32 v5, 0
	v_mov_b32_e32 v4, v165
	v_mov_b32_e32 v3, v165
	v_mov_b32_e32 v2, v165
	s_waitcnt lgkmcnt(0)
	s_barrier
	s_cbranch_scc1 .LBB0_225
	s_lshl_b32 s1, s16, 13
	s_add_i32 s16, s1, 0
	v_lshl_add_u64 v[168:169], s[4:5], 0, v[0:1]
	s_mul_i32 s1, s14, 0x7c
	s_mul_i32 s4, s17, 0x7c
	s_sub_i32 s1, s1, s4
	s_add_i32 s1, s1, 0
	s_lshl_b32 s0, s15, 8
	s_add_i32 s17, s1, 0xa360
	s_lshl_b32 s1, s13, 6
	v_lshlrev_b32_e32 v3, 3, v75
	v_xor_b32_e32 v74, 0x80000000, v74
	s_sub_i32 s0, s0, s1
	v_mov_b32_e32 v162, v1
	v_mov_b32_e32 v163, v1
	v_mov_b32_e32 v2, 0
	s_add_i32 s8, s13, 4
	s_lshl_b32 s9, s15, 11
	s_add_i32 s15, s12, 7
	v_mov_b32_e32 v75, v74
	v_mov_b32_e32 v76, v74
	v_mov_b32_e32 v77, v74
	s_add_i32 s18, s0, 0x4040
	s_mov_b32 s19, 0
	v_lshlrev_b32_e32 v0, 1, v3
	s_mov_b32 s21, 0
	v_mov_b64_e32 v[164:165], v[162:163]
	v_mov_b32_e32 v3, v2
	v_mov_b32_e32 v4, v2
	v_mov_b32_e32 v5, v2
	v_mov_b32_e32 v6, v2
	v_mov_b32_e32 v7, v2
	v_mov_b32_e32 v8, v2
	v_mov_b32_e32 v9, v2
	v_mov_b32_e32 v10, v2
	v_mov_b32_e32 v11, v2
	v_mov_b32_e32 v12, v2
	v_mov_b32_e32 v13, v2
	v_mov_b32_e32 v14, v2
	v_mov_b32_e32 v15, v2
	v_mov_b32_e32 v16, v2
	v_mov_b32_e32 v17, v2
	v_mov_b32_e32 v18, v2
	v_mov_b32_e32 v19, v2
	v_mov_b32_e32 v20, v2
	v_mov_b32_e32 v21, v2
	v_mov_b32_e32 v22, v2
	v_mov_b32_e32 v23, v2
	v_mov_b32_e32 v24, v2
	v_mov_b32_e32 v25, v2
	v_mov_b32_e32 v26, v2
	v_mov_b32_e32 v27, v2
	v_mov_b32_e32 v28, v2
	v_mov_b32_e32 v29, v2
	v_mov_b32_e32 v30, v2
	v_mov_b32_e32 v31, v2
	v_mov_b32_e32 v32, v2
	v_mov_b32_e32 v33, v2
	v_mov_b32_e32 v34, v2
	v_mov_b32_e32 v35, v2
	v_mov_b32_e32 v36, v2
	v_mov_b32_e32 v37, v2
	v_mov_b32_e32 v38, v2
	v_mov_b32_e32 v39, v2
	v_mov_b32_e32 v40, v2
	v_mov_b32_e32 v41, v2
	v_mov_b32_e32 v42, v2
	v_mov_b32_e32 v43, v2
	v_mov_b32_e32 v44, v2
	v_mov_b32_e32 v45, v2
	v_mov_b32_e32 v46, v2
	v_mov_b32_e32 v47, v2
	v_mov_b32_e32 v48, v2
	v_mov_b32_e32 v49, v2
	v_mov_b32_e32 v50, v2
	v_mov_b32_e32 v51, v2
	v_mov_b32_e32 v52, v2
	v_mov_b32_e32 v53, v2
	v_mov_b32_e32 v70, v2
	v_mov_b32_e32 v71, v2
	v_mov_b32_e32 v72, v2
	v_mov_b32_e32 v73, v2
	v_mov_b32_e32 v78, v2
	v_mov_b32_e32 v79, v2
	v_mov_b32_e32 v80, v2
	v_mov_b32_e32 v81, v2
	v_mov_b32_e32 v82, v2
	v_mov_b32_e32 v83, v2
	v_mov_b32_e32 v84, v2
	v_mov_b32_e32 v85, v2
	.p2align 6
